# prompt SSM scan: output stores batched 4 chunks per burst (register rotation), ring waits only on 2 of 4 chunks (vmcnt 9 / 15)
# speedup vs baseline: 1.0061x; 1.0001x over previous
.LBB0_87:
	v_add_u32_e32 v11, s3, v162
	v_add_u32_e32 v184, s3, v136
	v_add_u32_e32 v20, 96, v11
	v_add_u32_e32 v21, 96, v184
	v_add_u32_e32 v22, 104, v184
	v_mov_b32_e32 v18, s10
	v_mov_b32_e32 v19, s8
	v_add_u32_e32 v23, 0xffffe060, v11
	v_add_u32_e32 v24, 0xffffe060, v184
	v_cmp_gt_i32_e32 vcc, s26, v20
	v_cmp_gt_i32_e64 s[0:1], s26, v21
	v_cmp_gt_i32_e64 s[4:5], s26, v22
	v_ashrrev_i32_e32 v26, 31, v20
	v_ashrrev_i32_e32 v27, 31, v21
	v_mov_b32_e32 v12, s11
	v_mov_b32_e32 v13, s9
	v_add_u32_e32 v25, 0xffffe068, v184
	v_ashrrev_i32_e32 v28, 31, v22
	v_cndmask_b32_e32 v54, v18, v19, vcc
	v_cndmask_b32_e64 v56, v18, v19, s[0:1]
	v_cndmask_b32_e64 v58, v18, v19, s[4:5]
	v_cndmask_b32_e32 v18, v23, v20, vcc
	v_cndmask_b32_e32 v19, 0, v26, vcc
	v_cndmask_b32_e64 v20, v24, v21, s[0:1]
	v_cndmask_b32_e64 v21, 0, v27, s[0:1]
	v_cndmask_b32_e32 v55, v12, v13, vcc
	v_cndmask_b32_e64 v57, v12, v13, s[0:1]
	v_cndmask_b32_e64 v60, v25, v22, s[4:5]
	v_cndmask_b32_e64 v61, 0, v28, s[4:5]
	v_lshlrev_b64 v[62:63], 14, v[18:19]
	v_lshlrev_b64 v[64:65], 14, v[20:21]
	s_nop 0
	v_mov_b64_e32 v[108:109], v[100:101]
	v_cndmask_b32_e64 v59, v12, v13, s[4:5]
	v_lshlrev_b64 v[60:61], 14, v[60:61]
	v_lshl_add_u64 v[54:55], v[54:55], 0, v[62:63]
	v_lshl_add_u64 v[56:57], v[56:57], 0, v[64:65]
	v_mov_b64_e32 v[112:113], v[104:105]
	v_mov_b64_e32 v[106:107], v[98:99]
	v_mov_b32_e32 v133, v125
	v_lshl_add_u64 v[58:59], v[58:59], 0, v[60:61]
	v_lshl_add_u64 v[200:201], v[54:55], 0, s[36:37]
	v_lshl_add_u64 v[202:203], v[56:57], 0, s[36:37]
	v_mov_b64_e32 v[110:111], v[102:103]
	v_lshl_add_u64 v[204:205], v[58:59], 0, s[36:37]
	v_lshl_add_u64 v[200:201], v[200:201], 0, v[124:125]
	v_lshl_add_u64 v[202:203], v[202:203], 0, v[132:133]
	v_mov_b32_e32 v10, v178
	v_mov_b32_e32 v182, v156
	v_mov_b32_e32 v180, v150
	s_add_i32 m0, s100, 0x1000
	s_nop 0
	global_load_lds_dword v[174:175], off
	s_nop 0
	s_nop 0
	v_lshl_add_u64 v[204:205], v[204:205], 0, v[132:133]
	s_add_i32 m0, s100, 0x3f0
	s_nop 0
	global_load_lds_dwordx4 v[200:201], off offset:16
	s_add_i32 m0, s100, 0x0
	s_nop 0
	global_load_lds_dwordx4 v[200:201], off
	s_nop 0
	s_nop 0
	s_nop 0
	s_add_i32 s98, s98, 0x1400
	s_cmp_eq_u32 s98, 0x7800
	s_cselect_b32 s98, 0, s98
	s_add_i32 s100, s99, s98
	s_cmp_lt_i32 s3, 0
	s_cbranch_scc1 .Lssm_skip
	v_pk_mul_f32 v[6:7], v[6:7], v[10:11] op_sel_hi:[1,0]
	v_pk_mul_f32 v[8:9], v[8:9], v[10:11] op_sel_hi:[1,0]
	v_pk_mul_f32 v[2:3], v[10:11], v[2:3] op_sel_hi:[0,1]
	v_pk_mul_f32 v[4:5], v[10:11], v[4:5] op_sel_hi:[0,1]
	v_cvt_pk_bf16_f32 v50, v6, v7
	v_cvt_pk_bf16_f32 v51, v8, v9
	v_cvt_pk_bf16_f32 v52, v2, v3
	v_cvt_pk_bf16_f32 v53, v4, v5
	v_mov_b32_e32 v186, v177
	v_mov_b32_e32 v187, v176
	v_mfma_f32_32x32x16_bf16 v[2:17], v[50:53], v[94:97], 0
	v_mov_b32_e32 v188, v165
	v_mov_b32_e32 v189, v164
	v_add_u32_e32 v197, 0x800, v191
	v_add_u32_e32 v196, 0xa00, v191
	v_add_u32_e32 v195, 0x1000, v191
	v_add_u32_e32 v194, 0x1400, v191
	v_add_u32_e32 v163, 0x1800, v191
	v_mfma_f32_32x32x16_bf16 v[34:49], v[50:53], v[90:93], 0
	s_nop 3
	v_mov_b32_e32 v198, v2
	v_mov_b32_e32 v2, v4
	v_mov_b32_e32 v4, v6
	v_mov_b32_e32 v6, v8
	v_add_u32_e32 v193, 0x1a00, v191
	v_add_u32_e32 v137, 0x1c00, v191
	s_nop 1
	v_mov_b32_e32 v199, v34
	v_mfma_f32_32x32x16_bf16 v[18:33], v[50:53], v[86:89], 0
	v_mov_b32_e32 v34, v3
	v_mov_b32_e32 v3, v36
	v_mov_b32_e32 v36, v5
	v_mov_b32_e32 v5, v38
	v_mov_b32_e32 v38, v7
	v_mov_b32_e32 v7, v40
	v_mov_b32_e32 v8, v41
	v_mfma_f32_32x32x16_bf16 v[50:65], v[50:53], v[82:85], 0
	v_mov_b32_e32 v40, v10
	v_mov_b32_e32 v41, v42
	v_mov_b32_e32 v10, v43
	v_mov_b32_e32 v42, v12
	v_mov_b32_e32 v43, v44
	v_mov_b32_e32 v12, v45
	v_mov_b32_e32 v44, v14
	v_mov_b32_e32 v45, v46
	v_mov_b32_e32 v14, v47
	v_mov_b32_e32 v46, v16
	v_mov_b32_e32 v47, v48
	v_mov_b32_e32 v16, v49
	v_mov_b32_e32 v48, v18
	v_mov_b32_e32 v49, v50
	v_mov_b32_e32 v50, v19
	v_mov_b32_e32 v18, v20
	v_mov_b32_e32 v19, v52
	v_mov_b32_e32 v52, v21
	v_mov_b32_e32 v20, v22
	v_mov_b32_e32 v21, v54
	v_mov_b32_e32 v54, v23
	v_mov_b32_e32 v22, v24
	v_mov_b32_e32 v23, v56
	v_mov_b32_e32 v24, v57
	v_mov_b32_e32 v56, v26
	v_mov_b32_e32 v57, v58
	v_mov_b32_e32 v26, v59
	v_mov_b32_e32 v58, v28
	v_mov_b32_e32 v59, v60
	v_mov_b32_e32 v28, v61
	v_mov_b32_e32 v60, v30
	v_mov_b32_e32 v61, v62
	v_mov_b32_e32 v30, v63
	v_mov_b32_e32 v62, v32
	v_mov_b32_e32 v63, v64
	v_mov_b32_e32 v32, v65
	v_pk_fma_f32 v[64:65], v[148:149], v[176:177], v[198:199]
	v_pk_fma_f32 v[48:49], v[142:143], v[164:165], v[48:49]
	v_pk_fma_f32 v[64:65], v[160:161], v[186:187], v[64:65]
	v_pk_fma_f32 v[48:49], v[152:153], v[188:189], v[48:49]
	v_pk_fma_f32 v[34:35], v[148:149], v[64:65], v[34:35]
	v_pk_fma_f32 v[50:51], v[142:143], v[48:49], v[50:51]
	v_cvt_pk_bf16_f32 v164, v48, v49
	v_pk_fma_f32 v[34:35], v[160:161], v[64:65], v[34:35] op_sel:[0,1,0] op_sel_hi:[1,0,1]
	v_pk_fma_f32 v[48:49], v[152:153], v[48:49], v[50:51] op_sel:[0,1,0] op_sel_hi:[1,0,1]
	v_pk_fma_f32 v[2:3], v[148:149], v[34:35], v[2:3]
	v_pk_fma_f32 v[18:19], v[142:143], v[48:49], v[18:19]
	v_pk_fma_f32 v[2:3], v[160:161], v[34:35], v[2:3] op_sel:[0,1,0] op_sel_hi:[1,0,1]
	v_pk_fma_f32 v[18:19], v[152:153], v[48:49], v[18:19] op_sel:[0,1,0] op_sel_hi:[1,0,1]
	v_cvt_pk_bf16_f32 v50, v34, v35
	v_pk_fma_f32 v[34:35], v[148:149], v[2:3], v[36:37]
	v_pk_fma_f32 v[36:37], v[142:143], v[18:19], v[52:53]
	v_cvt_pk_bf16_f32 v51, v48, v49
	v_cvt_pk_bf16_f32 v48, v2, v3
	v_cvt_pk_bf16_f32 v49, v18, v19
	v_pk_fma_f32 v[2:3], v[160:161], v[2:3], v[34:35] op_sel:[0,1,0] op_sel_hi:[1,0,1]
	v_pk_fma_f32 v[18:19], v[152:153], v[18:19], v[36:37] op_sel:[0,1,0] op_sel_hi:[1,0,1]
	v_pk_fma_f32 v[4:5], v[148:149], v[2:3], v[4:5]
	v_pk_fma_f32 v[20:21], v[142:143], v[18:19], v[20:21]
	v_cvt_pk_bf16_f32 v34, v2, v3
	v_pk_fma_f32 v[2:3], v[160:161], v[2:3], v[4:5] op_sel:[0,1,0] op_sel_hi:[1,0,1]
	v_pk_fma_f32 v[4:5], v[152:153], v[18:19], v[20:21] op_sel:[0,1,0] op_sel_hi:[1,0,1]
	v_cvt_pk_bf16_f32 v35, v18, v19
	v_pk_fma_f32 v[18:19], v[148:149], v[2:3], v[38:39]
	v_pk_fma_f32 v[20:21], v[142:143], v[4:5], v[54:55]
	ds_write2_b32 v191, v34, v35 offset0:204 offset1:236
	v_cvt_pk_bf16_f32 v34, v2, v3
	v_cvt_pk_bf16_f32 v35, v4, v5
	v_pk_fma_f32 v[2:3], v[160:161], v[2:3], v[18:19] op_sel:[0,1,0] op_sel_hi:[1,0,1]
	v_pk_fma_f32 v[4:5], v[152:153], v[4:5], v[20:21] op_sel:[0,1,0] op_sel_hi:[1,0,1]
	v_pk_fma_f32 v[6:7], v[148:149], v[2:3], v[6:7]
	v_pk_fma_f32 v[18:19], v[142:143], v[4:5], v[22:23]
	v_cvt_pk_bf16_f32 v20, v2, v3
	v_cvt_pk_bf16_f32 v21, v4, v5
	v_pk_fma_f32 v[2:3], v[158:159], v[2:3], v[6:7] op_sel:[0,0,1] op_sel_hi:[1,1,0]
	v_pk_fma_f32 v[4:5], v[146:147], v[4:5], v[18:19] op_sel:[0,0,1] op_sel_hi:[1,1,0]
	ds_write2_b32 v197, v20, v21 offset0:100 offset1:132
	v_pk_mov_b32 v[6:7], v[2:3], v[2:3] op_sel:[1,0]
	v_pk_fma_f32 v[8:9], v[148:149], v[2:3], v[8:9]
	v_pk_mov_b32 v[18:19], v[4:5], v[4:5] op_sel:[1,0]
	v_pk_fma_f32 v[20:21], v[142:143], v[4:5], v[24:25]
	v_cvt_pk_bf16_f32 v22, v6, v7
	v_pk_fma_f32 v[2:3], v[166:167], v[2:3], v[8:9] op_sel:[0,0,1] op_sel_hi:[1,1,0]
	v_cvt_pk_bf16_f32 v8, v18, v19
	v_pk_fma_f32 v[4:5], v[168:169], v[4:5], v[20:21] op_sel:[0,0,1] op_sel_hi:[1,1,0]
	v_pk_fma_f32 v[6:7], v[148:149], v[2:3], v[40:41]
	ds_write2_b32 v197, v22, v8 offset0:168 offset1:200
	v_pk_fma_f32 v[8:9], v[142:143], v[4:5], v[56:57]
	v_cvt_pk_bf16_f32 v18, v2, v3
	v_cvt_pk_bf16_f32 v19, v4, v5
	v_pk_fma_f32 v[2:3], v[158:159], v[2:3], v[6:7] op_sel:[0,0,1] op_sel_hi:[1,1,0]
	v_pk_fma_f32 v[4:5], v[146:147], v[4:5], v[8:9] op_sel:[0,0,1] op_sel_hi:[1,1,0]
	ds_write2_b32 v196, v18, v19 offset0:108 offset1:140
	v_pk_mov_b32 v[6:7], v[2:3], v[2:3] op_sel:[1,0]
	v_pk_fma_f32 v[8:9], v[148:149], v[2:3], v[10:11]
	v_pk_mov_b32 v[10:11], v[4:5], v[4:5] op_sel:[1,0]
	v_pk_fma_f32 v[18:19], v[142:143], v[4:5], v[26:27]
	v_cvt_pk_bf16_f32 v20, v6, v7
	v_pk_fma_f32 v[2:3], v[166:167], v[2:3], v[8:9] op_sel:[0,0,1] op_sel_hi:[1,1,0]
	v_cvt_pk_bf16_f32 v8, v10, v11
	v_pk_fma_f32 v[4:5], v[168:169], v[4:5], v[18:19] op_sel:[0,0,1] op_sel_hi:[1,1,0]
	v_pk_fma_f32 v[6:7], v[148:149], v[2:3], v[42:43]
	ds_write2_b32 v195, v20, v8 offset0:64 offset1:96
	v_pk_fma_f32 v[8:9], v[142:143], v[4:5], v[58:59]
	v_cvt_pk_bf16_f32 v10, v2, v3
	v_cvt_pk_bf16_f32 v11, v4, v5
	v_pk_fma_f32 v[2:3], v[158:159], v[2:3], v[6:7] op_sel:[0,0,1] op_sel_hi:[1,1,0]
	v_pk_fma_f32 v[4:5], v[146:147], v[4:5], v[8:9] op_sel:[0,0,1] op_sel_hi:[1,1,0]
	ds_write2_b32 v195, v10, v11 offset0:132 offset1:164
	v_pk_mov_b32 v[6:7], v[2:3], v[2:3] op_sel:[1,0]
	v_pk_fma_f32 v[8:9], v[148:149], v[2:3], v[12:13]
	v_pk_mov_b32 v[10:11], v[4:5], v[4:5] op_sel:[1,0]
	v_pk_fma_f32 v[12:13], v[142:143], v[4:5], v[28:29]
	v_cvt_pk_bf16_f32 v18, v6, v7
	v_pk_fma_f32 v[2:3], v[166:167], v[2:3], v[8:9] op_sel:[0,0,1] op_sel_hi:[1,1,0]
	v_cvt_pk_bf16_f32 v8, v10, v11
	v_pk_fma_f32 v[4:5], v[168:169], v[4:5], v[12:13] op_sel:[0,0,1] op_sel_hi:[1,1,0]
	v_pk_fma_f32 v[6:7], v[148:149], v[2:3], v[44:45]
	ds_write2_b32 v195, v18, v8 offset0:200 offset1:232
	v_pk_fma_f32 v[8:9], v[142:143], v[4:5], v[60:61]
	v_cvt_pk_bf16_f32 v10, v2, v3
	v_cvt_pk_bf16_f32 v11, v4, v5
	v_pk_fma_f32 v[2:3], v[158:159], v[2:3], v[6:7] op_sel:[0,0,1] op_sel_hi:[1,1,0]
	v_pk_fma_f32 v[4:5], v[146:147], v[4:5], v[8:9] op_sel:[0,0,1] op_sel_hi:[1,1,0]
	ds_write2_b32 v194, v10, v11 offset0:12 offset1:44
	v_pk_mov_b32 v[6:7], v[2:3], v[2:3] op_sel:[1,0]
	v_pk_fma_f32 v[8:9], v[148:149], v[2:3], v[14:15]
	v_pk_mov_b32 v[10:11], v[4:5], v[4:5] op_sel:[1,0]
	v_pk_fma_f32 v[12:13], v[142:143], v[4:5], v[30:31]
	v_cvt_pk_bf16_f32 v14, v6, v7
	v_pk_fma_f32 v[2:3], v[166:167], v[2:3], v[8:9] op_sel:[0,0,1] op_sel_hi:[1,1,0]
	v_cvt_pk_bf16_f32 v8, v10, v11
	v_pk_fma_f32 v[4:5], v[168:169], v[4:5], v[12:13] op_sel:[0,0,1] op_sel_hi:[1,1,0]
	v_pk_fma_f32 v[6:7], v[148:149], v[2:3], v[46:47]
	ds_write2_b32 v163, v14, v8 offset0:96 offset1:128
	v_pk_fma_f32 v[8:9], v[142:143], v[4:5], v[62:63]
	v_cvt_pk_bf16_f32 v10, v2, v3
	v_cvt_pk_bf16_f32 v11, v4, v5
	v_pk_fma_f32 v[2:3], v[158:159], v[2:3], v[6:7] op_sel:[0,0,1] op_sel_hi:[1,1,0]
	v_pk_fma_f32 v[4:5], v[146:147], v[4:5], v[8:9] op_sel:[0,0,1] op_sel_hi:[1,1,0]
	v_cvt_pk_bf16_f32 v133, v64, v65
	ds_write2_b32 v163, v10, v11 offset0:164 offset1:196
	v_pk_mov_b32 v[6:7], v[2:3], v[2:3] op_sel:[1,0]
	v_pk_fma_f32 v[8:9], v[148:149], v[2:3], v[16:17]
	v_pk_mov_b32 v[10:11], v[4:5], v[4:5] op_sel:[1,0]
	v_pk_fma_f32 v[12:13], v[142:143], v[4:5], v[32:33]
	ds_write2_b32 v191, v133, v164 offset1:32
	v_cvt_pk_bf16_f32 v6, v6, v7
	v_pk_fma_f32 v[176:177], v[166:167], v[2:3], v[8:9] op_sel:[0,0,1] op_sel_hi:[1,1,0]
	v_cvt_pk_bf16_f32 v2, v10, v11
	v_pk_fma_f32 v[164:165], v[168:169], v[4:5], v[12:13] op_sel:[0,0,1] op_sel_hi:[1,1,0]
	v_cvt_pk_bf16_f32 v3, v176, v177
	ds_write2_b32 v193, v6, v2 offset0:104 offset1:136
	v_cvt_pk_bf16_f32 v2, v164, v165
	ds_write2_b32 v191, v50, v51 offset0:68 offset1:100
	ds_write2_b32 v191, v48, v49 offset0:136 offset1:168
	ds_write2_b32 v197, v34, v35 offset0:32 offset1:64
	ds_write2_b32 v137, v3, v2 offset0:44 offset1:76
	s_waitcnt lgkmcnt(0)
	ds_read_b128 v[18:21], v192
	ds_read_b128 v[22:25], v192 offset:4352
	ds_read_b128 v[26:29], v192 offset:64
	ds_read_b128 v[30:33], v192 offset:4416
	ds_read_b128 v[34:37], v192 offset:128
	ds_read_b128 v[38:41], v192 offset:4480
	ds_read_b128 v[42:45], v192 offset:192
	ds_read_b128 v[46:49], v192 offset:4544
	s_waitcnt lgkmcnt(6)
	v_mfma_f32_16x16x32_bf16 v[2:5], v[74:77], v[18:21], 0
	v_mfma_f32_16x16x32_bf16 v[6:9], v[74:77], v[22:25], 0
	s_waitcnt lgkmcnt(4)
	v_mfma_f32_16x16x32_bf16 v[2:5], v[78:81], v[26:29], v[2:5]
	v_mfma_f32_16x16x32_bf16 v[6:9], v[78:81], v[30:33], v[6:9]
	s_waitcnt lgkmcnt(2)
	v_mfma_f32_16x16x32_bf16 v[2:5], v[70:73], v[34:37], v[2:5]
	v_mfma_f32_16x16x32_bf16 v[6:9], v[70:73], v[38:41], v[6:9]
	s_waitcnt lgkmcnt(0)
	v_mfma_f32_16x16x32_bf16 v[2:5], v[66:69], v[42:45], v[2:5]
	v_mfma_f32_16x16x32_bf16 v[6:9], v[66:69], v[46:49], v[6:9]
	s_and_b32 s101, s3, 0x30
	s_cmp_eq_u32 s101, 0x30
	s_cbranch_scc1 .Lssm_w9
	s_cmp_eq_u32 s101, 0x20
	s_cbranch_scc0 .Lssm_wdone
	s_waitcnt vmcnt(15)
	s_branch .Lssm_wdone
.Lssm_w9:
	s_waitcnt vmcnt(9)
.Lssm_wdone:
	v_add_u32_e32 v208, s100, v206
	v_add_u32_e32 v209, s100, v207
	v_add_u32_e32 v214, s100, v210
	v_add_u32_e32 v215, s100, v211
	v_add_u32_e32 v216, s100, v212
	v_add_u32_e32 v217, s100, v213
	ds_read_b128 v[118:121], v208
	ds_read_b128 v[114:117], v208 offset:1024
	ds_read_b128 v[102:105], v214
	ds_read_b128 v[98:101], v215
	ds_read_b32 v178, v209 offset:4096
	ds_read_b32 v156, v216 offset:4096
	ds_read_b32 v150, v217 offset:4096
	v_mul_f32_e64 v10, v110, v182
	v_mul_f32_e64 v11, v111, v182
	v_pk_mul_f32 v[12:13], v[112:113], v[182:183] op_sel_hi:[1,0]
	v_pk_fma_f32 v[2:3], v[144:145], v[10:11], v[2:3]
	v_pk_fma_f32 v[4:5], v[140:141], v[12:13], v[4:5]
	v_mul_f32_e32 v10, 0x3d372713, v2
	v_mul_f32_e32 v11, 0x3d372713, v3
	v_mul_f32_e32 v12, 0x3d372713, v4
	v_mul_f32_e32 v13, 0x3d372713, v5
	v_mul_f32_e32 v10, v2, v10
	v_mul_f32_e32 v11, v3, v11
	v_mul_f32_e32 v12, v4, v12
	v_mul_f32_e32 v13, v5, v13
	v_fma_f32 v10, v2, v10, v2
	v_fma_f32 v11, v3, v11, v3
	v_fma_f32 v12, v4, v12, v4
	v_fma_f32 v13, v5, v13, v5
	v_mul_f32_e32 v10, 0x3f4c422a, v10
	v_mul_f32_e32 v11, 0x3f4c422a, v11
	v_mul_f32_e32 v12, 0x3f4c422a, v12
	v_mul_f32_e32 v13, 0x3f4c422a, v13
	v_mul_f32_e32 v10, -2.0, v10
	v_mul_f32_e32 v11, -2.0, v11
	v_mul_f32_e32 v12, -2.0, v12
	v_mul_f32_e32 v13, -2.0, v13
	v_mul_f32_e32 v10, 0x3fb8aa3b, v10
	v_mul_f32_e32 v11, 0x3fb8aa3b, v11
	v_mul_f32_e32 v12, 0x3fb8aa3b, v12
	v_mul_f32_e32 v13, 0x3fb8aa3b, v13
	v_exp_f32_e32 v10, v10
	v_exp_f32_e32 v11, v11
	v_exp_f32_e32 v12, v12
	v_exp_f32_e32 v13, v13
	v_add_f32_e32 v10, 1.0, v10
	v_add_f32_e32 v11, 1.0, v11
	v_add_f32_e32 v12, 1.0, v12
	v_add_f32_e32 v13, 1.0, v13
	v_rcp_f32_e32 v10, v10
	v_rcp_f32_e32 v11, v11
	v_rcp_f32_e32 v12, v12
	v_rcp_f32_e32 v13, v13
	v_ashrrev_i32_e32 v185, 31, v184
	v_pk_mul_f32 v[2:3], v[2:3], v[10:11]
	s_add_i32 s3, s3, 16
	v_pk_mul_f32 v[4:5], v[4:5], v[12:13]
	v_cvt_pk_bf16_f32 v2, v2, v3
	v_cvt_pk_bf16_f32 v3, v4, v5
	v_pk_mul_f32 v[4:5], v[106:107], v[180:181] op_sel_hi:[1,0]
	v_pk_mul_f32 v[12:13], v[108:109], v[180:181] op_sel_hi:[1,0]
	v_pk_fma_f32 v[4:5], v[144:145], v[4:5], v[6:7]
	v_pk_fma_f32 v[8:9], v[140:141], v[12:13], v[8:9]
	v_mul_f32_e32 v6, 0x3d372713, v4
	v_mul_f32_e32 v6, v4, v6
	v_fma_f32 v6, v4, v6, v4
	v_mul_f32_e32 v6, 0x3f4c422a, v6
	v_mul_f32_e32 v6, -2.0, v6
	v_mul_f32_e32 v6, 0x3fb8aa3b, v6
	v_exp_f32_e32 v10, v6
	v_mul_f32_e32 v6, 0x3d372713, v5
	v_mul_f32_e32 v12, 0x3d372713, v8
	v_mul_f32_e32 v13, 0x3d372713, v9
	v_mul_f32_e32 v6, v5, v6
	v_mul_f32_e32 v12, v8, v12
	v_mul_f32_e32 v13, v9, v13
	v_fma_f32 v6, v5, v6, v5
	v_fma_f32 v12, v8, v12, v8
	v_fma_f32 v13, v9, v13, v9
	v_mul_f32_e32 v6, 0x3f4c422a, v6
	v_mul_f32_e32 v12, 0x3f4c422a, v12
	v_mul_f32_e32 v13, 0x3f4c422a, v13
	v_mul_f32_e32 v6, -2.0, v6
	v_mul_f32_e32 v12, -2.0, v12
	v_mul_f32_e32 v13, -2.0, v13
	v_mul_f32_e32 v6, 0x3fb8aa3b, v6
	v_mul_f32_e32 v12, 0x3fb8aa3b, v12
	v_mul_f32_e32 v13, 0x3fb8aa3b, v13
	v_exp_f32_e32 v11, v6
	v_exp_f32_e32 v12, v12
	v_exp_f32_e32 v13, v13
	v_add_f32_e32 v10, 1.0, v10
	v_add_f32_e32 v11, 1.0, v11
	v_add_f32_e32 v12, 1.0, v12
	v_add_f32_e32 v13, 1.0, v13
	v_rcp_f32_e32 v10, v10
	v_rcp_f32_e32 v11, v11
	v_rcp_f32_e32 v12, v12
	v_rcp_f32_e32 v13, v13
	v_mov_b64_e32 v[234:235], v[230:231]
	v_mov_b64_e32 v[236:237], v[232:233]
	v_mov_b64_e32 v[230:231], v[226:227]
	v_mov_b64_e32 v[232:233], v[228:229]
	v_mov_b64_e32 v[226:227], v[222:223]
	v_mov_b64_e32 v[228:229], v[224:225]
	v_mov_b64_e32 v[222:223], v[2:3]
	v_pk_mul_f32 v[2:3], v[4:5], v[10:11]
	v_pk_mul_f32 v[4:5], v[8:9], v[12:13]
	v_cvt_pk_bf16_f32 v2, v2, v3
	v_cvt_pk_bf16_f32 v3, v4, v5
	v_mov_b64_e32 v[224:225], v[2:3]
	s_and_b32 s101, s3, 0x30
	s_cmp_lg_u32 s101, 0
	s_cbranch_scc1 .Lssm_noflush
	v_lshlrev_b64 v[238:239], 13, v[184:185]
	v_lshl_add_u64 v[238:239], v[138:139], 0, v[238:239]
	global_store_dwordx2 v[238:239], v[222:223], off
	v_add_u32_e32 v238, 8, v184
	v_ashrrev_i32_e32 v239, 31, v238
	v_lshlrev_b64 v[238:239], 13, v[238:239]
	v_lshl_add_u64 v[238:239], v[138:139], 0, v[238:239]
	global_store_dwordx2 v[238:239], v[224:225], off
	v_add_u32_e32 v238, 0xfffffff0, v184
	v_ashrrev_i32_e32 v239, 31, v238
	v_lshlrev_b64 v[238:239], 13, v[238:239]
	v_lshl_add_u64 v[238:239], v[138:139], 0, v[238:239]
	global_store_dwordx2 v[238:239], v[226:227], off
	v_add_u32_e32 v238, 0xfffffff8, v184
	v_ashrrev_i32_e32 v239, 31, v238
	v_lshlrev_b64 v[238:239], 13, v[238:239]
	v_lshl_add_u64 v[238:239], v[138:139], 0, v[238:239]
	global_store_dwordx2 v[238:239], v[228:229], off
	v_add_u32_e32 v238, 0xffffffe0, v184
	v_ashrrev_i32_e32 v239, 31, v238
	v_lshlrev_b64 v[238:239], 13, v[238:239]
	v_lshl_add_u64 v[238:239], v[138:139], 0, v[238:239]
	global_store_dwordx2 v[238:239], v[230:231], off
	v_add_u32_e32 v238, 0xffffffe8, v184
	v_ashrrev_i32_e32 v239, 31, v238
	v_lshlrev_b64 v[238:239], 13, v[238:239]
	v_lshl_add_u64 v[238:239], v[138:139], 0, v[238:239]
	global_store_dwordx2 v[238:239], v[232:233], off
	v_add_u32_e32 v238, 0xffffffd0, v184
	v_ashrrev_i32_e32 v239, 31, v238
	v_lshlrev_b64 v[238:239], 13, v[238:239]
	v_lshl_add_u64 v[238:239], v[138:139], 0, v[238:239]
	global_store_dwordx2 v[238:239], v[234:235], off
	v_add_u32_e32 v238, 0xffffffd8, v184
	v_ashrrev_i32_e32 v239, 31, v238
	v_lshlrev_b64 v[238:239], 13, v[238:239]
	v_lshl_add_u64 v[238:239], v[138:139], 0, v[238:239]
	global_store_dwordx2 v[238:239], v[236:237], off
.Lssm_noflush:
	s_waitcnt lgkmcnt(0)
	v_mov_b64_e32 v[6:7], v[118:119]
	v_mov_b64_e32 v[2:3], v[114:115]
	v_lshl_add_u64 v[170:171], v[170:171], 0, 64
	v_lshl_add_u64 v[172:173], v[172:173], 0, 64
	v_lshl_add_u64 v[174:175], v[174:175], 0, 64
	s_cmpk_lg_i32 s3, 0x7f0
	v_mov_b64_e32 v[8:9], v[120:121]
	v_mov_b64_e32 v[4:5], v[116:117]
	s_cbranch_scc1 .LBB0_87
	s_branch .Lssm_after

.Lssm_after:
	s_waitcnt vmcnt(0)
	v_lshlrev_b64 v[238:239], 13, v[184:185]
	v_lshl_add_u64 v[238:239], v[138:139], 0, v[238:239]
	global_store_dwordx2 v[238:239], v[222:223], off
	v_add_u32_e32 v238, 8, v184
	v_ashrrev_i32_e32 v239, 31, v238
	v_lshlrev_b64 v[238:239], 13, v[238:239]
	v_lshl_add_u64 v[238:239], v[138:139], 0, v[238:239]
	global_store_dwordx2 v[238:239], v[224:225], off
	v_add_u32_e32 v238, 0xfffffff0, v184
	v_ashrrev_i32_e32 v239, 31, v238
	v_lshlrev_b64 v[238:239], 13, v[238:239]
	v_lshl_add_u64 v[238:239], v[138:139], 0, v[238:239]
	global_store_dwordx2 v[238:239], v[226:227], off
	v_add_u32_e32 v238, 0xfffffff8, v184
	v_ashrrev_i32_e32 v239, 31, v238
	v_lshlrev_b64 v[238:239], 13, v[238:239]
	v_lshl_add_u64 v[238:239], v[138:139], 0, v[238:239]
	global_store_dwordx2 v[238:239], v[228:229], off
	v_add_u32_e32 v238, 0xffffffe0, v184
	v_ashrrev_i32_e32 v239, 31, v238
	v_lshlrev_b64 v[238:239], 13, v[238:239]
	v_lshl_add_u64 v[238:239], v[138:139], 0, v[238:239]
	global_store_dwordx2 v[238:239], v[230:231], off
	v_add_u32_e32 v238, 0xffffffe8, v184
	v_ashrrev_i32_e32 v239, 31, v238
	v_lshlrev_b64 v[238:239], 13, v[238:239]
	v_lshl_add_u64 v[238:239], v[138:139], 0, v[238:239]
	global_store_dwordx2 v[238:239], v[232:233], off
	v_pk_mul_f32 v[2:3], v[118:119], v[178:179] op_sel_hi:[1,0]
	s_nop 0
	v_cvt_pk_bf16_f32 v40, v2, v3
	v_pk_mul_f32 v[2:3], v[120:121], v[178:179] op_sel_hi:[1,0]
	s_nop 0
	v_cvt_pk_bf16_f32 v41, v2, v3
	v_pk_mul_f32 v[2:3], v[178:179], v[114:115] op_sel_hi:[0,1]
	v_cvt_pk_bf16_f32 v42, v2, v3
	v_pk_mul_f32 v[2:3], v[178:179], v[116:117] op_sel_hi:[0,1]
	v_cvt_pk_bf16_f32 v43, v2, v3
	v_or_b32_e32 v2, s27, v1
	v_ashrrev_i32_e32 v3, 31, v2
	v_mfma_f32_32x32x16_bf16 v[4:19], v[40:43], v[94:97], 0
	v_lshlrev_b64 v[2:3], 14, v[2:3]
	v_or_b32_e32 v2, s2, v2
	v_or_b32_e32 v2, v2, v122
	v_lshlrev_b64 v[38:39], 2, v[2:3]
	v_lshl_add_u64 v[36:37], s[40:41], 0, v[38:39]
	s_nop 6
	v_mov_b32_e32 v2, v4
	v_mfma_f32_32x32x16_bf16 v[20:35], v[40:43], v[90:93], 0
	s_nop 11
	v_mov_b32_e32 v3, v20
	v_pk_fma_f32 v[2:3], v[148:149], v[176:177], v[2:3]
	v_mov_b32_e32 v4, v21
	v_pk_fma_f32 v[2:3], v[158:159], v[176:177], v[2:3] op_sel:[0,0,1] op_sel_hi:[1,1,0]
	s_nop 0
	v_pk_fma_f32 v[4:5], v[148:149], v[2:3], v[4:5]
	v_pk_mov_b32 v[44:45], v[2:3], v[2:3] op_sel:[1,0]
	v_pk_fma_f32 v[2:3], v[160:161], v[2:3], v[4:5] op_sel:[0,0,1] op_sel_hi:[1,1,0]
	v_mov_b32_e32 v4, v6
	v_mov_b32_e32 v5, v22
	v_pk_fma_f32 v[4:5], v[148:149], v[2:3], v[4:5]
	v_cvt_pk_bf16_f32 v44, v44, v45
	v_cvt_pk_bf16_f32 v45, v2, v3
	v_pk_fma_f32 v[2:3], v[160:161], v[2:3], v[4:5] op_sel:[0,1,0] op_sel_hi:[1,0,1]
	v_mov_b32_e32 v22, v7
	v_pk_fma_f32 v[4:5], v[148:149], v[2:3], v[22:23]
	v_cvt_pk_bf16_f32 v46, v2, v3
	v_pk_fma_f32 v[2:3], v[160:161], v[2:3], v[4:5] op_sel:[0,1,0] op_sel_hi:[1,0,1]
	v_mov_b32_e32 v4, v8
	v_mov_b32_e32 v5, v24
	v_pk_fma_f32 v[4:5], v[148:149], v[2:3], v[4:5]
	v_cvt_pk_bf16_f32 v47, v2, v3
	v_pk_fma_f32 v[2:3], v[160:161], v[2:3], v[4:5] op_sel:[0,1,0] op_sel_hi:[1,0,1]
	v_mov_b32_e32 v24, v9
	v_pk_fma_f32 v[4:5], v[148:149], v[2:3], v[24:25]
	v_cvt_pk_bf16_f32 v48, v2, v3
	v_pk_fma_f32 v[2:3], v[160:161], v[2:3], v[4:5] op_sel:[0,1,0] op_sel_hi:[1,0,1]
	v_mov_b32_e32 v4, v10
	v_mov_b32_e32 v5, v26
	v_pk_fma_f32 v[4:5], v[148:149], v[2:3], v[4:5]
	v_cvt_pk_bf16_f32 v49, v2, v3
	v_pk_fma_f32 v[2:3], v[160:161], v[2:3], v[4:5] op_sel:[0,1,0] op_sel_hi:[1,0,1]
	v_mov_b32_e32 v26, v11
	v_pk_fma_f32 v[4:5], v[148:149], v[2:3], v[26:27]
	v_cvt_pk_bf16_f32 v50, v2, v3
	v_pk_fma_f32 v[2:3], v[160:161], v[2:3], v[4:5] op_sel:[0,1,0] op_sel_hi:[1,0,1]
	v_mov_b32_e32 v4, v12
	v_mov_b32_e32 v5, v28
	v_pk_fma_f32 v[4:5], v[148:149], v[2:3], v[4:5]
	v_cvt_pk_bf16_f32 v51, v2, v3
	v_pk_fma_f32 v[2:3], v[160:161], v[2:3], v[4:5] op_sel:[0,1,0] op_sel_hi:[1,0,1]
	v_mov_b32_e32 v28, v13
	v_pk_fma_f32 v[4:5], v[148:149], v[2:3], v[28:29]
	v_cvt_pk_bf16_f32 v52, v2, v3
	v_pk_fma_f32 v[2:3], v[160:161], v[2:3], v[4:5] op_sel:[0,1,0] op_sel_hi:[1,0,1]
	v_mov_b32_e32 v4, v14
	v_mov_b32_e32 v5, v30
	v_pk_fma_f32 v[4:5], v[148:149], v[2:3], v[4:5]
	v_cvt_pk_bf16_f32 v53, v2, v3
	v_pk_fma_f32 v[2:3], v[160:161], v[2:3], v[4:5] op_sel:[0,1,0] op_sel_hi:[1,0,1]
	v_mov_b32_e32 v30, v15
	v_pk_fma_f32 v[4:5], v[148:149], v[2:3], v[30:31]
	v_cvt_pk_bf16_f32 v54, v2, v3
	v_pk_fma_f32 v[2:3], v[160:161], v[2:3], v[4:5] op_sel:[0,1,0] op_sel_hi:[1,0,1]
	v_mov_b32_e32 v4, v16
	v_mov_b32_e32 v5, v32
	v_pk_fma_f32 v[4:5], v[148:149], v[2:3], v[4:5]
	v_cvt_pk_bf16_f32 v55, v2, v3
	v_pk_fma_f32 v[2:3], v[160:161], v[2:3], v[4:5] op_sel:[0,1,0] op_sel_hi:[1,0,1]
	v_mov_b32_e32 v32, v17
	v_pk_fma_f32 v[4:5], v[148:149], v[2:3], v[32:33]
	v_mov_b32_e32 v22, v18
	v_pk_fma_f32 v[20:21], v[160:161], v[2:3], v[4:5] op_sel:[0,1,0] op_sel_hi:[1,0,1]
	v_mov_b32_e32 v23, v34
	v_pk_fma_f32 v[22:23], v[148:149], v[20:21], v[22:23]
	v_cvt_pk_bf16_f32 v57, v20, v21
	v_pk_fma_f32 v[20:21], v[160:161], v[20:21], v[22:23] op_sel:[0,1,0] op_sel_hi:[1,0,1]
	v_mov_b32_e32 v34, v19
	v_pk_fma_f32 v[18:19], v[148:149], v[20:21], v[34:35]
	v_cvt_pk_bf16_f32 v56, v2, v3
	v_mfma_f32_32x32x16_bf16 v[2:17], v[40:43], v[86:89], 0
	v_cvt_pk_bf16_f32 v58, v20, v21
	v_fma_f32 v34, v160, v21, v18
	v_fma_f32 v35, v161, v20, v19
	v_cvt_pk_bf16_f32 v59, v34, v35
	v_mfma_f32_32x32x16_bf16 v[18:33], v[40:43], v[82:85], 0
	s_nop 6
	v_mov_b32_e32 v40, v2
	s_nop 3
	v_mov_b32_e32 v41, v18
	v_pk_fma_f32 v[40:41], v[142:143], v[164:165], v[40:41]
	s_nop 0
	v_pk_fma_f32 v[40:41], v[146:147], v[164:165], v[40:41] op_sel:[0,0,1] op_sel_hi:[1,1,0]
	s_nop 0
	v_pk_mov_b32 v[42:43], v[40:41], v[40:41] op_sel:[1,0]
	s_nop 0
	v_cvt_pk_bf16_f32 v2, v42, v43
	ds_write2_b32 v191, v44, v2 offset1:32
	v_mov_b32_e32 v2, v19
	v_pk_fma_f32 v[2:3], v[142:143], v[40:41], v[2:3]
	v_mov_b32_e32 v19, v20
	v_pk_fma_f32 v[2:3], v[152:153], v[40:41], v[2:3] op_sel:[0,0,1] op_sel_hi:[1,1,0]
	v_mov_b32_e32 v20, v5
	v_cvt_pk_bf16_f32 v18, v2, v3
	ds_write2_b32 v191, v45, v18 offset0:68 offset1:100
	v_mov_b32_e32 v18, v4
	v_pk_fma_f32 v[18:19], v[142:143], v[2:3], v[18:19]
	s_nop 0
	v_pk_fma_f32 v[2:3], v[152:153], v[2:3], v[18:19] op_sel:[0,1,0] op_sel_hi:[1,0,1]
	s_nop 0
	v_cvt_pk_bf16_f32 v4, v2, v3
	ds_write2_b32 v191, v46, v4 offset0:136 offset1:168
	v_pk_fma_f32 v[4:5], v[142:143], v[2:3], v[20:21]
	s_nop 0
	v_pk_fma_f32 v[2:3], v[152:153], v[2:3], v[4:5] op_sel:[0,1,0] op_sel_hi:[1,0,1]
	v_mov_b32_e32 v5, v22
	v_cvt_pk_bf16_f32 v4, v2, v3
	ds_write2_b32 v191, v47, v4 offset0:204 offset1:236
	v_mov_b32_e32 v4, v6
	v_pk_fma_f32 v[4:5], v[142:143], v[2:3], v[4:5]
	v_mov_b32_e32 v22, v7
	v_pk_fma_f32 v[2:3], v[152:153], v[2:3], v[4:5] op_sel:[0,1,0] op_sel_hi:[1,0,1]
	s_nop 0
	v_cvt_pk_bf16_f32 v4, v2, v3
	ds_write2_b32 v197, v48, v4 offset0:32 offset1:64
	v_pk_fma_f32 v[4:5], v[142:143], v[2:3], v[22:23]
	s_nop 0
	v_pk_fma_f32 v[2:3], v[152:153], v[2:3], v[4:5] op_sel:[0,1,0] op_sel_hi:[1,0,1]
	v_mov_b32_e32 v5, v24
	v_cvt_pk_bf16_f32 v4, v2, v3
	ds_write2_b32 v197, v49, v4 offset0:100 offset1:132
	v_mov_b32_e32 v4, v8
	v_pk_fma_f32 v[4:5], v[142:143], v[2:3], v[4:5]
	v_mov_b32_e32 v24, v9
	v_pk_fma_f32 v[2:3], v[152:153], v[2:3], v[4:5] op_sel:[0,1,0] op_sel_hi:[1,0,1]
	s_nop 0
	v_cvt_pk_bf16_f32 v4, v2, v3
	ds_write2_b32 v197, v50, v4 offset0:168 offset1:200
	v_pk_fma_f32 v[4:5], v[142:143], v[2:3], v[24:25]
	s_nop 0
	v_pk_fma_f32 v[2:3], v[152:153], v[2:3], v[4:5] op_sel:[0,1,0] op_sel_hi:[1,0,1]
	v_mov_b32_e32 v5, v26
	v_cvt_pk_bf16_f32 v4, v2, v3
	ds_write2_b32 v196, v51, v4 offset0:108 offset1:140
	v_mov_b32_e32 v4, v10
	v_pk_fma_f32 v[4:5], v[142:143], v[2:3], v[4:5]
	v_mov_b32_e32 v26, v11
	v_pk_fma_f32 v[2:3], v[152:153], v[2:3], v[4:5] op_sel:[0,1,0] op_sel_hi:[1,0,1]
	s_nop 0
	v_cvt_pk_bf16_f32 v4, v2, v3
	ds_write2_b32 v195, v52, v4 offset0:64 offset1:96
	v_pk_fma_f32 v[4:5], v[142:143], v[2:3], v[26:27]
	s_nop 0
	v_pk_fma_f32 v[2:3], v[152:153], v[2:3], v[4:5] op_sel:[0,1,0] op_sel_hi:[1,0,1]
	v_mov_b32_e32 v5, v28
	v_cvt_pk_bf16_f32 v4, v2, v3
	ds_write2_b32 v195, v53, v4 offset0:132 offset1:164
	v_mov_b32_e32 v4, v12
	v_pk_fma_f32 v[4:5], v[142:143], v[2:3], v[4:5]
	v_mov_b32_e32 v28, v13
	v_pk_fma_f32 v[2:3], v[152:153], v[2:3], v[4:5] op_sel:[0,1,0] op_sel_hi:[1,0,1]
	s_nop 0
	v_cvt_pk_bf16_f32 v4, v2, v3
	ds_write2_b32 v195, v54, v4 offset0:200 offset1:232
	v_pk_fma_f32 v[4:5], v[142:143], v[2:3], v[28:29]
	s_nop 0
	v_pk_fma_f32 v[2:3], v[152:153], v[2:3], v[4:5] op_sel:[0,1,0] op_sel_hi:[1,0,1]
	v_mov_b32_e32 v5, v30
	v_cvt_pk_bf16_f32 v4, v2, v3
	ds_write2_b32 v194, v55, v4 offset0:12 offset1:44
	v_mov_b32_e32 v4, v14
	v_pk_fma_f32 v[4:5], v[142:143], v[2:3], v[4:5]
	v_mov_b32_e32 v30, v15
	v_pk_fma_f32 v[2:3], v[152:153], v[2:3], v[4:5] op_sel:[0,1,0] op_sel_hi:[1,0,1]
	s_nop 0
	v_cvt_pk_bf16_f32 v4, v2, v3
	ds_write2_b32 v163, v56, v4 offset0:96 offset1:128
	v_pk_fma_f32 v[4:5], v[142:143], v[2:3], v[30:31]
	s_nop 0
	v_pk_fma_f32 v[2:3], v[152:153], v[2:3], v[4:5] op_sel:[0,1,0] op_sel_hi:[1,0,1]
	v_mov_b32_e32 v5, v32
	v_cvt_pk_bf16_f32 v4, v2, v3
	ds_write2_b32 v163, v57, v4 offset0:164 offset1:196
	v_mov_b32_e32 v4, v16
	v_pk_fma_f32 v[4:5], v[142:143], v[2:3], v[4:5]
	v_mov_b32_e32 v32, v17
	v_pk_fma_f32 v[2:3], v[152:153], v[2:3], v[4:5] op_sel:[0,1,0] op_sel_hi:[1,0,1]
	s_nop 0
	v_cvt_pk_bf16_f32 v4, v2, v3
	ds_write2_b32 v193, v58, v4 offset0:104 offset1:136
	v_pk_fma_f32 v[4:5], v[142:143], v[2:3], v[32:33]
	s_nop 0
	v_pk_fma_f32 v[18:19], v[152:153], v[2:3], v[4:5] op_sel:[0,1,0] op_sel_hi:[1,0,1]
	s_nop 0
	v_cvt_pk_bf16_f32 v2, v18, v19
	ds_write2_b32 v137, v59, v2 offset0:44 offset1:76
	s_waitcnt lgkmcnt(0)
	ds_read_b128 v[2:5], v192
	ds_read_b128 v[6:9], v192 offset:64
	s_waitcnt lgkmcnt(1)
	v_mfma_f32_16x16x32_bf16 v[2:5], v[74:77], v[2:5], 0
	s_waitcnt lgkmcnt(0)
	v_mfma_f32_16x16x32_bf16 v[2:5], v[78:81], v[6:9], v[2:5]
	ds_read_b128 v[6:9], v192 offset:128
	ds_read_b128 v[10:13], v192 offset:192
	s_waitcnt lgkmcnt(1)
	v_mfma_f32_16x16x32_bf16 v[2:5], v[70:73], v[6:9], v[2:5]
	s_waitcnt lgkmcnt(0)
	v_mfma_f32_16x16x32_bf16 v[2:5], v[66:69], v[10:13], v[2:5]
	ds_read_b128 v[6:9], v192 offset:4352
	ds_read_b128 v[10:13], v192 offset:4416
	s_waitcnt lgkmcnt(1)
	v_mfma_f32_16x16x32_bf16 v[6:9], v[74:77], v[6:9], 0
	s_waitcnt lgkmcnt(0)
	v_mfma_f32_16x16x32_bf16 v[6:9], v[78:81], v[10:13], v[6:9]
	ds_read_b128 v[10:13], v192 offset:4480
	ds_read_b128 v[14:17], v192 offset:4544
	s_waitcnt lgkmcnt(0)
	s_waitcnt lgkmcnt(1)
	v_mfma_f32_16x16x32_bf16 v[6:9], v[70:73], v[10:13], v[6:9]
	s_waitcnt lgkmcnt(0)
	v_mfma_f32_16x16x32_bf16 v[6:9], v[66:69], v[14:17], v[6:9]
	s_waitcnt vmcnt(3)
	v_pk_mul_f32 v[10:11], v[156:157], v[102:103] op_sel_hi:[0,1]
	v_pk_mul_f32 v[12:13], v[156:157], v[104:105] op_sel_hi:[0,1]
	v_pk_fma_f32 v[2:3], v[144:145], v[10:11], v[2:3]
	v_pk_fma_f32 v[4:5], v[140:141], v[12:13], v[4:5]
	v_mul_f32_e32 v10, 0x3d372713, v2
	v_mul_f32_e32 v11, 0x3d372713, v3
	v_mul_f32_e32 v12, 0x3d372713, v4
	v_mul_f32_e32 v13, 0x3d372713, v5
	v_mul_f32_e32 v10, v2, v10
	v_mul_f32_e32 v11, v3, v11
	v_mul_f32_e32 v12, v4, v12
	v_mul_f32_e32 v13, v5, v13
	v_fma_f32 v10, v2, v10, v2
	v_fma_f32 v11, v3, v11, v3
	v_fma_f32 v12, v4, v12, v4
	v_fma_f32 v13, v5, v13, v5
	v_mul_f32_e32 v10, 0x3f4c422a, v10
	v_mul_f32_e32 v11, 0x3f4c422a, v11
	v_mul_f32_e32 v12, 0x3f4c422a, v12
	v_mul_f32_e32 v13, 0x3f4c422a, v13
	v_mul_f32_e32 v10, -2.0, v10
	v_mul_f32_e32 v11, -2.0, v11
	v_mul_f32_e32 v12, -2.0, v12
	v_mul_f32_e32 v13, -2.0, v13
	v_mul_f32_e32 v10, 0x3fb8aa3b, v10
	v_mul_f32_e32 v11, 0x3fb8aa3b, v11
	v_mul_f32_e32 v12, 0x3fb8aa3b, v12
	v_mul_f32_e32 v13, 0x3fb8aa3b, v13
	v_exp_f32_e32 v10, v10
	v_exp_f32_e32 v11, v11
	v_exp_f32_e32 v12, v12
	v_exp_f32_e32 v13, v13
	v_add_f32_e32 v10, 1.0, v10
	v_add_f32_e32 v11, 1.0, v11
	v_add_f32_e32 v12, 1.0, v12
	v_add_f32_e32 v13, 1.0, v13
	v_rcp_f32_e32 v10, v10
	v_rcp_f32_e32 v11, v11
	v_rcp_f32_e32 v12, v12
	v_rcp_f32_e32 v13, v13
	s_add_i32 s24, s25, s24
	v_pk_mul_f32 v[2:3], v[2:3], v[10:11]
	v_or_b32_e32 v10, 0x7f0, v136
	v_pk_mul_f32 v[4:5], v[4:5], v[12:13]
	v_cvt_pk_bf16_f32 v2, v2, v3
	v_cvt_pk_bf16_f32 v3, v4, v5
	s_waitcnt vmcnt(2)
	v_pk_mul_f32 v[4:5], v[150:151], v[98:99] op_sel_hi:[0,1]
	v_pk_fma_f32 v[4:5], v[144:145], v[4:5], v[6:7]
	v_ashrrev_i32_e32 v11, 31, v10
	v_mul_f32_e32 v6, 0x3d372713, v4
	v_mul_f32_e32 v6, v4, v6
	v_fma_f32 v6, v4, v6, v4
	v_mul_f32_e32 v6, 0x3f4c422a, v6
	v_mul_f32_e32 v6, -2.0, v6
	v_mul_f32_e32 v6, 0x3fb8aa3b, v6
	v_exp_f32_e32 v12, v6
	v_mul_f32_e32 v6, 0x3d372713, v5
	v_mul_f32_e32 v6, v5, v6
	v_fma_f32 v6, v5, v6, v5
	v_mul_f32_e32 v6, 0x3f4c422a, v6
	v_mul_f32_e32 v6, -2.0, v6
	v_mul_f32_e32 v6, 0x3fb8aa3b, v6
	v_exp_f32_e32 v13, v6
	v_lshlrev_b64 v[6:7], 13, v[10:11]
	v_add_f32_e32 v10, 1.0, v12
	v_rcp_f32_e32 v10, v10
	v_add_f32_e32 v11, 1.0, v13
	v_pk_mul_f32 v[12:13], v[150:151], v[100:101] op_sel_hi:[0,1]
	v_pk_fma_f32 v[8:9], v[140:141], v[12:13], v[8:9]
	v_rcp_f32_e32 v11, v11
	v_mul_f32_e32 v12, 0x3d372713, v8
	v_mul_f32_e32 v13, 0x3d372713, v9
	v_mul_f32_e32 v12, v8, v12
	v_mul_f32_e32 v13, v9, v13
	v_fma_f32 v12, v8, v12, v8
	v_fma_f32 v13, v9, v13, v9
	v_mul_f32_e32 v12, 0x3f4c422a, v12
	v_mul_f32_e32 v13, 0x3f4c422a, v13
	v_mul_f32_e32 v12, -2.0, v12
	v_mul_f32_e32 v13, -2.0, v13
	v_mul_f32_e32 v12, 0x3fb8aa3b, v12
	v_mul_f32_e32 v13, 0x3fb8aa3b, v13
	v_exp_f32_e32 v12, v12
	v_exp_f32_e32 v13, v13
	v_lshl_add_u64 v[6:7], v[138:139], 0, v[6:7]
	global_store_dwordx2 v[6:7], v[2:3], off
	v_add_f32_e32 v12, 1.0, v12
	v_add_f32_e32 v13, 1.0, v13
	v_rcp_f32_e32 v12, v12
	v_rcp_f32_e32 v13, v13
	v_or_b32_e32 v6, 0x7f8, v136
	v_pk_mul_f32 v[2:3], v[4:5], v[10:11]
	v_ashrrev_i32_e32 v7, 31, v6
	v_pk_mul_f32 v[4:5], v[8:9], v[12:13]
	v_cvt_pk_bf16_f32 v2, v2, v3
	v_cvt_pk_bf16_f32 v3, v4, v5
	v_lshlrev_b64 v[4:5], 13, v[6:7]
	v_lshl_add_u64 v[4:5], v[138:139], 0, v[4:5]
	global_store_dwordx2 v[4:5], v[2:3], off
	v_lshl_add_u64 v[2:3], s[42:43], 0, v[38:39]
	s_cmpk_gt_i32 s24, 0x1ff
	global_store_dword v[36:37], v34, off
	global_store_dword v[2:3], v35, off
	global_store_dword v[36:37], v18, off offset:128
	global_store_dword v[2:3], v19, off offset:128
	s_cbranch_scc0 .LBB0_86
